# attention: + scalar-base K/V tile loads (no per-iteration address VALU), interleaved row-sum chains, v_perm V transposes
# baseline (speedup 1.0000x reference)
; #define STOREKV(buf) do { *(u32x4*)(Kt + (buf) * KT_BYTES + kr0 * KROW + kc0 * 16) = xk0; \
;         if (tid < 256) { *(u32x4*)(Kt + (buf) * KT_BYTES + kr1 * KROW + kc1 * 16) = xa; } \
;         else { tstore_pair(Vt + (buf) * VT_BYTES, VROW, pos64(2 * va), vc8, xa, xb); } } while (0)
; __device__ __forceinline__ void attn_unit2(const bf16_t* Qm, const bf16_t* KVm, const bf16_t* P1, bf16_t* OP, int q0, int h, int klat, int nlat, int kctx, int nt, uchar* lds, bool nostore = false) {
;     ...
;     const int kr0 = tid / 12, kc0 = tid % 12, kr1 = (512 + tid) / 12, kc1 = (512 + tid) % 12;
;     const int tv = tid - 256, va = tv >> 3, vc8 = tv & 7;
;     u32x4 xk0, xa = (u32x4){0u, 0u, 0u, 0u}, xb = xa;
;     ...
;     LOADKV(0); STOREKV(0);
;     __syncthreads();
;     float mA = -1e30f, mB = -1e30f, lA = 0.f, lB = 0.f; f32x16 oA0 = {}, oA1 = {}, oB0 = {}, oB1 = {};
.LBB0_1098:
	s_andn2_saveexec_b64 s[4:5], s[4:5]
	v_add3_u32 v3, 0, v224, v225
	ds_write_b128 v3, v[186:189]
	v_and_b32_e32 v3, 0x7ffffff2, v223
	v_or3_b32 v3, v9, v3, v8
	v_lshlrev_b32_e32 v7, 1, v3
	s_or_b64 exec, exec, s[4:5]
	v_and_b32_e32 v3, 31, v10
	v_mul_u32_u24_e32 v8, 0xd0, v3
	v_add3_u32 v226, 0, v8, v0
	v_and_b32_e32 v8, 64, v210
	v_xor_b32_e32 v0, 32, v210
	v_add_u32_e32 v8, 64, v8
	v_cmp_lt_i32_e32 vcc, v0, v8
	s_lshl_b32 s6, s9, 8
	s_lshl_b32 s74, s13, 1
	v_cndmask_b32_e32 v0, v210, v0, vcc
	s_add_u32 s4, s92, s74
	v_lshlrev_b32_e32 v227, 2, v0
	v_lshlrev_b32_e32 v0, 6, v3
	v_mov_b32_e32 v3, v1
	s_addc_u32 s5, s93, 0
	v_sub_u32_e32 v228, v226, v0
	v_lshl_add_u64 v[196:197], v[2:3], 1, s[30:31]
	v_mov_b32_e32 v3, v11
	v_lshlrev_b32_e32 v0, 3, v5
	v_lshl_add_u64 v[198:199], v[2:3], 1, s[4:5]
	v_cmp_lt_i32_e64 s[42:43], 7, v5
	v_ashrrev_i32_e32 v3, 31, v0
	v_mov_b32_e32 v2, v0
	v_mov_b32_e32 v5, v1
	v_mov_b32_e32 v14, v1
	v_mov_b32_e32 v15, v1
	v_lshl_add_u64 v[200:201], v[0:1], 1, s[30:31]
	v_lshl_add_u64 v[202:203], v[2:3], 1, s[4:5]
	v_add3_u32 v230, 0, v6, v7
	v_lshl_add_u64 v[204:205], s[4:5], 0, v[4:5]
	v_mov_b32_e32 v0, v1
	v_mov_b32_e32 v2, v1
	v_mov_b32_e32 v3, v1
	v_mov_b32_e32 v4, v1
	v_mov_b32_e32 v6, v1
	v_mov_b32_e32 v7, v1
	v_mov_b32_e32 v8, v1
	v_mov_b32_e32 v9, v1
	v_mov_b32_e32 v10, v1
	v_mov_b32_e32 v11, v1
	v_mov_b32_e32 v12, v1
	v_mov_b32_e32 v13, v1
	s_waitcnt lgkmcnt(1)
	v_mov_b64_e32 v[64:65], v[14:15]
	v_mov_b64_e32 v[48:49], v[14:15]
	v_mov_b64_e32 v[32:33], v[14:15]
	v_mov_b64_e32 v[62:63], v[12:13]
	v_mov_b64_e32 v[60:61], v[10:11]
	v_mov_b64_e32 v[58:59], v[8:9]
	v_mov_b64_e32 v[56:57], v[6:7]
	v_mov_b64_e32 v[54:55], v[4:5]
	v_mov_b64_e32 v[52:53], v[2:3]
	v_mov_b64_e32 v[50:51], v[0:1]
	v_mov_b64_e32 v[46:47], v[12:13]
	v_mov_b64_e32 v[44:45], v[10:11]
	v_mov_b64_e32 v[42:43], v[8:9]
	v_mov_b64_e32 v[40:41], v[6:7]
	v_mov_b64_e32 v[38:39], v[4:5]
	v_mov_b64_e32 v[36:37], v[2:3]
	v_mov_b64_e32 v[34:35], v[0:1]
	v_mov_b64_e32 v[30:31], v[12:13]
	v_mov_b64_e32 v[28:29], v[10:11]
	v_mov_b64_e32 v[26:27], v[8:9]
	v_mov_b64_e32 v[24:25], v[6:7]
	v_mov_b64_e32 v[22:23], v[4:5]
	v_mov_b64_e32 v[20:21], v[2:3]
	v_mov_b64_e32 v[18:19], v[0:1]
	v_mov_b64_e32 v[16:17], v[14:15]
	s_mov_b32 s9, 0
	s_add_i32 s13, s6, 0x6040
	s_add_i32 s22, s22, 64
	v_mov_b32_e32 v231, 0
	v_mov_b32_e32 v232, 0
	v_mov_b32_e32 v233, 0
	v_mov_b32_e32 v229, 0
	v_mov_b64_e32 v[14:15], v[12:13]
	v_mov_b64_e32 v[12:13], v[10:11]
	v_mov_b64_e32 v[10:11], v[8:9]
	v_mov_b64_e32 v[8:9], v[6:7]
	v_mov_b64_e32 v[6:7], v[4:5]
	v_mov_b64_e32 v[4:5], v[2:3]
	v_mov_b64_e32 v[2:3], v[0:1]
	v_mov_b32_e32 v197, 0x800
	v_mov_b32_e32 v196, s16
	v_cndmask_b32_e64 v196, v197, v196, s[38:39]
	v_mad_u32_u24 v196, v221, v196, v194
	v_mov_b32_e32 v198, s16
	v_cndmask_b32_e64 v198, v197, v198, s[42:43]
	v_mad_u32_u24 v198, v195, v198, v225
	v_and_b32_e32 v199, 7, v206
	v_lshlrev_b32_e32 v199, 4, v199
	v_lshl_add_u32 v199, v223, 11, v199
	v_add_u32_e32 v199, 0x400, v199
	v_cndmask_b32_e64 v197, v198, v199, s[40:41]
	v_and_b32_e32 v216, 63, v206
	v_mul_u32_u24_e32 v216, 0xd0, v216
	v_bfe_u32 v217, v206, 6, 1
	v_mul_u32_u24_e32 v217, 0x3400, v217
	v_add_u32_e32 v216, v216, v217
	v_mov_b32_e32 v190, 0x3f80
	v_mov_b32_e32 v191, 0
	v_mov_b32_e32 v192, 0
	v_mov_b32_e32 v193, 0
	ds_write_b128 v216, v[190:193] offset:192
	s_waitcnt lgkmcnt(0)
	v_mov_b32_e32 v190, 0
	v_mov_b32_e32 v216, 0
	v_mov_b32_e32 v217, 0
	v_mov_b32_e32 v218, 0
	v_mov_b32_e32 v219, 0
	s_waitcnt lgkmcnt(0)
	s_barrier
	s_branch .LBB0_1103

; #define MFMA32(a, b, c) __builtin_amdgcn_mfma_f32_32x32x16_bf16((a), (b), (c), 0, 0, 0)
; __device__ __forceinline__ void attn_unit2(const bf16_t* Qm, const bf16_t* KVm, const bf16_t* P1, bf16_t* OP, int q0, int h, int klat, int nlat, int kctx, int nt, uchar* lds, bool nostore = false) {
;     ...
;     for (int t = 0; t < nt; ++t) {
;         const int buf = t & 1;
;         if (t + 1 < nt) LOADKV(t + 1);
;         f32x16 sA0 = {}, sA1 = {}, sB0 = {}, sB1 = {};
;         { const uchar* kb = Kt + buf * KT_BYTES + l32 * KROW + hi * 16;
; #pragma unroll
;           for (int s = 0; s < 6; ++s) { const bf16x8 a0 = *(const bf16x8*)(kb + s * 32), a1 = *(const bf16x8*)(kb + 32 * KROW + s * 32);
;               sA0 = MFMA32(a0, qa[s], sA0); sA1 = MFMA32(a1, qa[s], sA1); sB0 = MFMA32(a0, qb[s], sB0); sB1 = MFMA32(a1, qb[s], sB1); } }
.LBB0_1102:
	v_add_f32_e32 v66, v98, v66
	v_add_f32_e32 v0, v0, v82
	v_add_f32_e32 v67, v128, v67
	v_add_f32_e32 v234, v114, v83
	v_add_f32_e32 v66, v67, v66
	v_add_f32_e32 v0, v234, v0
	v_add_f32_e32 v67, v100, v129
	v_add_f32_e32 v234, v115, v84
	v_add_f32_e32 v66, v67, v66
	v_add_f32_e32 v0, v234, v0
	v_add_f32_e32 v67, v101, v69
	v_add_f32_e32 v234, v116, v85
	v_add_f32_e32 v66, v67, v66
	v_add_f32_e32 v0, v234, v0
	v_add_f32_e32 v67, v102, v70
	v_add_f32_e32 v234, v117, v86
	v_add_f32_e32 v66, v67, v66
	v_add_f32_e32 v0, v234, v0
	v_add_f32_e32 v67, v103, v71
	v_add_f32_e32 v234, v118, v87
	v_add_f32_e32 v66, v67, v66
	v_add_f32_e32 v0, v234, v0
	v_add_f32_e32 v67, v104, v72
	v_add_f32_e32 v234, v119, v88
	v_add_f32_e32 v66, v67, v66
	v_add_f32_e32 v0, v234, v0
	v_add_f32_e32 v67, v105, v73
	v_add_f32_e32 v234, v120, v89
	v_add_f32_e32 v66, v67, v66
	v_add_f32_e32 v0, v234, v0
	v_add_f32_e32 v67, v106, v74
	v_add_f32_e32 v234, v121, v90
	v_add_f32_e32 v66, v67, v66
	v_add_f32_e32 v0, v234, v0
	v_add_f32_e32 v67, v107, v75
	v_add_f32_e32 v234, v122, v91
	v_add_f32_e32 v66, v67, v66
	v_add_f32_e32 v0, v234, v0
	v_add_f32_e32 v67, v108, v76
	v_add_f32_e32 v234, v123, v92
	v_add_f32_e32 v66, v67, v66
	v_add_f32_e32 v0, v234, v0
	v_add_f32_e32 v67, v109, v77
	v_add_f32_e32 v234, v124, v93
	v_add_f32_e32 v66, v67, v66
	v_add_f32_e32 v0, v234, v0
	v_add_f32_e32 v67, v110, v78
	v_add_f32_e32 v234, v125, v94
	v_add_f32_e32 v66, v67, v66
	v_add_f32_e32 v0, v234, v0
	v_add_f32_e32 v67, v111, v79
	v_add_f32_e32 v234, v126, v95
	v_add_f32_e32 v66, v67, v66
	v_add_f32_e32 v0, v234, v0
	v_add_f32_e32 v67, v112, v80
	v_add_f32_e32 v234, v127, v96
	v_add_f32_e32 v66, v67, v66
	v_add_f32_e32 v0, v234, v0
	v_add_f32_e32 v67, v113, v81
	v_add_f32_e32 v234, v99, v68
	v_add_f32_e32 v66, v67, v66
	v_add_f32_e32 v0, v234, v0
	v_add_f32_e32 v229, v229, v66
	s_add_i32 s9, s9, 1
	s_add_i32 s13, s13, 64
	s_add_i32 s22, s22, 64
	v_add_f32_e32 v231, v231, v0
	s_cmpk_eq_i32 s9, 0x84
	s_waitcnt lgkmcnt(0)
	s_barrier
	s_cbranch_scc1 .LBB0_1126
.LBB0_1103:
	s_cmpk_lg_i32 s9, 0x83
	s_cselect_b64 s[44:45], -1, 0
	s_cmpk_eq_i32 s9, 0x83
	s_cbranch_scc1 .LBB0_1117
	s_cmpk_lt_u32 s9, 0x7f
	s_cselect_b32 s6, s22, s13
	s_lshl_b32 s4, s6, 11
	s_add_u32 s4, s4, s74
	s_add_u32 s4, s92, s4
	s_addc_u32 s5, s93, 0
	s_mul_i32 s18, s6, s16
	s_add_u32 s18, s18, s82
	s_addc_u32 s19, s83, 0
	s_add_u32 s18, s18, s30
	s_addc_u32 s19, s19, s31
	s_mov_b64 exec, s[38:39]
	global_load_dwordx4 v[178:181], v196, s[18:19]
	s_not_b64 exec, exec
	global_load_dwordx4 v[178:181], v196, s[4:5]
	s_cmp_lg_u64 s[40:41], 0
	s_cbranch_scc1 .Latt_ldv
	s_mov_b64 exec, s[42:43]
	global_load_dwordx4 v[186:189], v197, s[18:19]
	s_not_b64 exec, exec
	global_load_dwordx4 v[186:189], v197, s[4:5]
	s_branch .Latt_lddone
.Latt_ldv:
	s_mov_b64 exec, -1
	global_load_dwordx4 v[182:185], v197, s[4:5] offset:2048
	global_load_dwordx4 v[186:189], v197, s[4:5]
.Latt_lddone:
	s_mov_b64 exec, -1

; #define MFMA32(a, b, c) __builtin_amdgcn_mfma_f32_32x32x16_bf16((a), (b), (c), 0, 0, 0)
; #define STOREKV(buf) do { *(u32x4*)(Kt + (buf) * KT_BYTES + kr0 * KROW + kc0 * 16) = xk0; \
;         if (tid < 256) { *(u32x4*)(Kt + (buf) * KT_BYTES + kr1 * KROW + kc1 * 16) = xa; } \
;         else { tstore_pair(Vt + (buf) * VT_BYTES, VROW, pos64(2 * va), vc8, xa, xb); } } while (0)
; __device__ __forceinline__ void attn_unit2(const bf16_t* Qm, const bf16_t* KVm, const bf16_t* P1, bf16_t* OP, int q0, int h, int klat, int nlat, int kctx, int nt, uchar* lds, bool nostore = false) {
;     ...
;         SOFTMAX_BLK(sA0, sA1, mA, lA, oA0, oA1);
;         SOFTMAX_BLK(sB0, sB1, mB, lB, oB0, oB1);
;         const uchar* vb = Vt + buf * VT_BYTES + l32 * VROW + hi * 16;
; #pragma unroll
;         for (int kk = 0; kk < 4; ++kk) {
;             const int r0 = 8 * (kk & 1);
;             const bf16x8 pa = (kk >> 1) ? pack8(sA1[r0], sA1[r0 + 1], sA1[r0 + 2], sA1[r0 + 3], sA1[r0 + 4], sA1[r0 + 5], sA1[r0 + 6], sA1[r0 + 7])
;                                         : pack8(sA0[r0], sA0[r0 + 1], sA0[r0 + 2], sA0[r0 + 3], sA0[r0 + 4], sA0[r0 + 5], sA0[r0 + 6], sA0[r0 + 7]);
;             const bf16x8 pb = (kk >> 1) ? pack8(sB1[r0], sB1[r0 + 1], sB1[r0 + 2], sB1[r0 + 3], sB1[r0 + 4], sB1[r0 + 5], sB1[r0 + 6], sB1[r0 + 7])
;                                         : pack8(sB0[r0], sB0[r0 + 1], sB0[r0 + 2], sB0[r0 + 3], sB0[r0 + 4], sB0[r0 + 5], sB0[r0 + 6], sB0[r0 + 7]);
;             const bf16x8 a0 = *(const bf16x8*)(vb + kk * 32), a1 = *(const bf16x8*)(vb + 32 * VROW + kk * 32);
;             oA0 = MFMA32(a0, pa, oA0); oA1 = MFMA32(a1, pa, oA1); oB0 = MFMA32(a0, pb, oB0); oB1 = MFMA32(a1, pb, oB1);
;         }
;         if (t + 1 < nt) STOREKV(buf ^ 1);
.LBB0_1121:
	s_mul_i32 s5, s4, 0x2400
	v_add_u32_e32 v242, s5, v228
	ds_read_b128 v[212:215], v242 offset:26624
	ds_read_b128 v[238:241], v242 offset:31232
	v_exp_f32_e32 v100, v100
	v_exp_f32_e32 v101, v101
	v_exp_f32_e32 v102, v102
	v_exp_f32_e32 v103, v103
	v_exp_f32_e32 v0, v114
	v_exp_f32_e32 v114, v115
	v_exp_f32_e32 v115, v116
	v_exp_f32_e32 v116, v117
	v_exp_f32_e32 v117, v118
	v_exp_f32_e32 v118, v119
	v_exp_f32_e32 v119, v120
	v_exp_f32_e32 v120, v121
	v_exp_f32_e32 v104, v104
	v_exp_f32_e32 v98, v98
	v_exp_f32_e32 v105, v105
	v_cvt_pk_bf16_f32 v234, v0, v114
	v_cvt_pk_bf16_f32 v235, v115, v116
	v_cvt_pk_bf16_f32 v236, v117, v118
	v_cvt_pk_bf16_f32 v237, v119, v120
	v_exp_f32_e32 v121, v122
	s_waitcnt lgkmcnt(1)
	v_mfma_f32_32x32x16_bf16 v[50:65], v[212:215], v[234:237], v[50:65]
	v_exp_f32_e32 v122, v123
	v_exp_f32_e32 v123, v124
	v_exp_f32_e32 v124, v125
	v_exp_f32_e32 v125, v126
	v_exp_f32_e32 v126, v127
	v_exp_f32_e32 v127, v128
	v_exp_f32_e32 v128, v99
	v_exp_f32_e32 v99, v129
	s_waitcnt lgkmcnt(0)
	v_mfma_f32_32x32x16_bf16 v[34:49], v[238:241], v[234:237], v[34:49]
	v_cvt_pk_bf16_f32 v234, v98, v128
	v_cvt_pk_bf16_f32 v235, v100, v101
	v_cvt_pk_bf16_f32 v236, v102, v103
	v_cvt_pk_bf16_f32 v237, v104, v105
	s_nop 1
	v_mfma_f32_32x32x16_bf16 v[18:33], v[212:215], v[234:237], v[18:33]
	ds_read_b128 v[212:215], v242 offset:26656
	v_exp_f32_e32 v106, v106
	v_mfma_f32_32x32x16_bf16 v[2:17], v[238:241], v[234:237], v[2:17]
	ds_read_b128 v[238:241], v242 offset:31264
	v_exp_f32_e32 v107, v107
	v_exp_f32_e32 v108, v108
	v_exp_f32_e32 v109, v109
	v_exp_f32_e32 v110, v110
	v_exp_f32_e32 v111, v111
	v_exp_f32_e32 v112, v112
	v_exp_f32_e32 v113, v113
	v_cvt_pk_bf16_f32 v234, v121, v122
	v_cvt_pk_bf16_f32 v235, v123, v124
	v_cvt_pk_bf16_f32 v236, v125, v126
	v_cvt_pk_bf16_f32 v237, v127, v99
	v_exp_f32_e32 v129, v68
	s_waitcnt lgkmcnt(1)
	v_mfma_f32_32x32x16_bf16 v[50:65], v[212:215], v[234:237], v[50:65]
	v_exp_f32_e32 v69, v69
	v_exp_f32_e32 v70, v70
	s_waitcnt lgkmcnt(0)
	v_mfma_f32_32x32x16_bf16 v[34:49], v[238:241], v[234:237], v[34:49]
	v_cvt_pk_bf16_f32 v234, v106, v107
	v_cvt_pk_bf16_f32 v235, v108, v109
	v_cvt_pk_bf16_f32 v236, v110, v111
	v_cvt_pk_bf16_f32 v237, v112, v113
	s_nop 1
	v_mfma_f32_32x32x16_bf16 v[18:33], v[212:215], v[234:237], v[18:33]
	ds_read_b128 v[212:215], v242 offset:26688
	v_exp_f32_e32 v71, v71
	v_exp_f32_e32 v82, v82
	v_mfma_f32_32x32x16_bf16 v[2:17], v[238:241], v[234:237], v[2:17]
	ds_read_b128 v[238:241], v242 offset:31296
	v_exp_f32_e32 v83, v83
	v_exp_f32_e32 v84, v84
	v_exp_f32_e32 v85, v85
	v_exp_f32_e32 v86, v86
	v_exp_f32_e32 v87, v87
	v_exp_f32_e32 v88, v88
	v_exp_f32_e32 v89, v89
	v_exp_f32_e32 v72, v72
	v_exp_f32_e32 v66, v66
	v_exp_f32_e32 v67, v67
	v_exp_f32_e32 v73, v73
	v_cvt_pk_bf16_f32 v234, v82, v83
	v_cvt_pk_bf16_f32 v235, v84, v85
	v_cvt_pk_bf16_f32 v236, v86, v87
	v_cvt_pk_bf16_f32 v237, v88, v89
	s_waitcnt lgkmcnt(1)
	s_nop 0
	v_mfma_f32_32x32x16_bf16 v[50:65], v[212:215], v[234:237], v[50:65]
	v_exp_f32_e32 v90, v90
	s_waitcnt lgkmcnt(0)
	v_mfma_f32_32x32x16_bf16 v[34:49], v[238:241], v[234:237], v[34:49]
	v_cvt_pk_bf16_f32 v234, v66, v67
	v_cvt_pk_bf16_f32 v235, v129, v69
	v_cvt_pk_bf16_f32 v236, v70, v71
	v_cvt_pk_bf16_f32 v237, v72, v73
	v_exp_f32_e32 v91, v91
	v_exp_f32_e32 v92, v92
	v_exp_f32_e32 v93, v93
	v_mfma_f32_32x32x16_bf16 v[18:33], v[212:215], v[234:237], v[18:33]
	ds_read_b128 v[212:215], v242 offset:26720
	v_exp_f32_e32 v94, v94
	v_exp_f32_e32 v95, v95
	v_exp_f32_e32 v96, v96
	v_exp_f32_e32 v68, v97
	v_mfma_f32_32x32x16_bf16 v[2:17], v[238:241], v[234:237], v[2:17]
	ds_read_b128 v[238:241], v242 offset:31328
	v_exp_f32_e32 v74, v74
	v_exp_f32_e32 v75, v75
	v_exp_f32_e32 v76, v76
	v_exp_f32_e32 v77, v77
	v_exp_f32_e32 v78, v78
	v_exp_f32_e32 v79, v79
	v_exp_f32_e32 v80, v80
	v_exp_f32_e32 v81, v81
	v_cvt_pk_bf16_f32 v234, v90, v91
	v_cvt_pk_bf16_f32 v235, v92, v93
	v_cvt_pk_bf16_f32 v236, v94, v95
	v_cvt_pk_bf16_f32 v237, v96, v68
	s_andn2_b64 vcc, exec, s[44:45]
	s_waitcnt lgkmcnt(1)
	v_mfma_f32_32x32x16_bf16 v[50:65], v[212:215], v[234:237], v[50:65]
	s_waitcnt lgkmcnt(0)
	v_mfma_f32_32x32x16_bf16 v[34:49], v[238:241], v[234:237], v[34:49]
	v_cvt_pk_bf16_f32 v234, v74, v75
	v_cvt_pk_bf16_f32 v235, v76, v77
	v_cvt_pk_bf16_f32 v236, v78, v79
	v_cvt_pk_bf16_f32 v237, v80, v81
	s_nop 1
	v_mfma_f32_32x32x16_bf16 v[18:33], v[212:215], v[234:237], v[18:33]
	v_mfma_f32_32x32x16_bf16 v[2:17], v[238:241], v[234:237], v[2:17]
	s_cbranch_vccnz .LBB0_1102
	s_xor_b32 s7, s4, 1
	s_mul_i32 s4, s7, 0x3400
	s_add_i32 s6, s4, 0
	v_add3_u32 v97, s6, v222, v194
	s_waitcnt vmcnt(2)
	ds_write_b128 v97, v[178:181]
	s_and_saveexec_b64 s[4:5], s[40:41]
	s_xor_b64 s[4:5], exec, s[4:5]
	s_cbranch_execz .LBB0_1124
	s_mulk_i32 s7, 0x2400
	v_add_u32_e32 v97, s7, v230
	s_mov_b32 s18, 0x5040100
	s_mov_b32 s19, 0x7060302
	v_add_u32_e32 v97, 0x6800, v97
	s_waitcnt vmcnt(0)
	v_perm_b32 v212, v182, v186, s18
	v_perm_b32 v213, v182, v186, s19
	ds_write2_b32 v97, v212, v213 offset1:36
	v_perm_b32 v212, v183, v187, s18
	v_perm_b32 v213, v183, v187, s19
	ds_write2_b32 v97, v212, v213 offset0:72 offset1:108
	v_perm_b32 v212, v184, v188, s18
	v_perm_b32 v213, v184, v188, s19
	ds_write2_b32 v97, v212, v213 offset0:144 offset1:180
	v_perm_b32 v212, v185, v189, s18
	v_perm_b32 v213, v185, v189, s19
	ds_write2_b32 v97, v212, v213 offset0:216 offset1:252
